# baseline (speedup 1.0000x reference)
.LBB0_1411:
	s_or_b64 exec, exec, s[0:1]
	s_cmpk_gt_i32 s79, 0x57
	s_cselect_b64 s[2:3], -1, 0
	s_xor_b64 s[4:5], s[8:9], -1
	s_or_b64 s[2:3], s[2:3], s[4:5]
	s_mov_b64 s[0:1], -1
	s_and_b64 vcc, exec, s[2:3]
	s_barrier
	s_cbranch_vccz .LBB0_1415
	s_movk_i32 s33, 0xcc0
	s_andn2_b64 vcc, exec, s[8:9]
	s_mov_b32 s52, s77
	s_cbranch_vccnz .LBB0_1414
	s_add_i32 s36, s79, 0xffffffa8
	s_movk_i32 s52, 0xa8
	s_movk_i32 s33, 0x9a8
	s_cmp_lt_u32 s36, 24
	s_cselect_b32 s33, 0x888, s33
	s_cmp_gt_u32 s36, 0x77
	s_cselect_b32 s33, 0x9d8, s33

.LBB0_1686:
	s_add_i32 s36, s79, 0xd90
	s_movk_i32 s52, 0x58
	s_movk_i32 s33, 0x10a8
	s_waitcnt vmcnt(0)
	s_barrier

.LBB0_1727:
	s_waitcnt vmcnt(1)
	v_mov_b32_e32 v52, v244
	v_mov_b32_e32 v0, 0
	s_andn2_b64 vcc, exec, s[2:3]
	v_lshlrev_b32_e32 v53, 4, v52
	v_ashrrev_i32_e32 v110, 4, v52
	v_mov_b32_e32 v1, 0
	v_mov_b32_e32 v2, 0
	v_mov_b32_e32 v3, 0
	v_mov_b32_e32 v4, 0
	v_mov_b32_e32 v5, 0
	v_mov_b32_e32 v6, 0
	v_mov_b32_e32 v7, 0
	v_mov_b32_e32 v8, 0
	v_mov_b32_e32 v9, 0
	v_mov_b32_e32 v10, 0
	v_mov_b32_e32 v11, 0
	v_mov_b32_e32 v12, 0
	v_mov_b32_e32 v13, 0
	v_mov_b32_e32 v14, 0
	v_mov_b32_e32 v15, 0
	v_mov_b32_e32 v16, 0
	v_mov_b32_e32 v17, 0
	v_mov_b32_e32 v18, 0
	v_mov_b32_e32 v19, 0
	v_mov_b32_e32 v20, 0
	v_mov_b32_e32 v21, 0
	v_mov_b32_e32 v22, 0
	v_mov_b32_e32 v23, 0
	v_mov_b32_e32 v24, 0
	v_mov_b32_e32 v25, 0
	v_mov_b32_e32 v26, 0
	v_mov_b32_e32 v27, 0
	v_mov_b32_e32 v28, 0
	v_mov_b32_e32 v29, 0
	v_mov_b32_e32 v30, 0
	v_mov_b32_e32 v31, 0
	v_mov_b32_e32 v32, 0
	v_mov_b32_e32 v33, 0
	v_mov_b32_e32 v34, 0
	v_mov_b32_e32 v35, 0
	v_mov_b32_e32 v36, 0
	v_mov_b32_e32 v37, 0
	v_mov_b32_e32 v38, 0
	v_mov_b32_e32 v39, 0
	v_mov_b32_e32 v40, 0
	v_mov_b32_e32 v41, 0
	v_mov_b32_e32 v42, 0
	v_mov_b32_e32 v43, 0
	v_mov_b32_e32 v44, 0
	v_mov_b32_e32 v45, 0
	v_mov_b32_e32 v46, 0
	v_mov_b32_e32 v47, 0
	s_waitcnt vmcnt(0)
	v_mov_b32_e32 v48, 0
	v_mov_b32_e32 v49, 0
	v_mov_b32_e32 v50, 0
	v_mov_b32_e32 v51, 0
	s_cbranch_vccnz .LBB0_1729
	s_add_i32 s98, s36, 0xfffffee0
	s_cmpk_lt_i32 s36, 0x9a8
	s_cselect_b32 s98, s36, s98
	s_add_i32 s99, s36, 0xffffff70
	s_cmpk_lt_i32 s36, 0x9c0
	s_cselect_b32 s98, s98, s99
	s_add_i32 s99, s36, 0xfffffc18
	s_cmpk_lt_i32 s36, 0xce0
	s_cselect_b32 s98, s98, s99
	s_cmp_eq_u32 s52, s77
	s_cselect_b32 s98, s36, s98
	s_add_i32 s0, s98, 0xffffff40
	s_ashr_i32 s0, s0, 5
	s_mul_hi_i32 s2, s0, 0x55555556
	s_lshr_b32 s3, s2, 31
	s_add_i32 s3, s2, s3
	s_mul_i32 s2, s3, 3
	s_sub_i32 s0, s0, s2
	s_lshl_b32 s6, s0, 1
	s_lshr_b32 s2, 32, s6
	s_and_b32 s1, s98, 31
	s_sub_i32 s5, 5, s6
	s_add_i32 s2, s2, -1
	s_lshr_b32 s5, s1, s5
	s_and_b32 s1, s2, s1
	s_lshl_b32 s2, s1, 6
	s_lshl_b32 s0, s0, 5
	s_and_b32 s1, s3, -8
	s_and_b32 s4, s3, 7
	s_add_i32 s0, s0, s1
	s_or_b32 s0, s0, s4
	s_lshl_b32 s3, s3, 8
	s_ashr_i32 s1, s0, 31
	s_and_b32 s3, s3, 0xfffff800
	s_lshr_b32 s7, 0x800, s6
	s_lshl_b64 s[0:1], s[0:1], 19
	s_addk_i32 s2, 0xff80
	s_or_b32 s3, s5, s3
	s_lshl_b32 s4, s4, 8
	v_readlane_b32 s10, v249, 10
	v_readlane_b32 s11, v249, 11
	s_add_u32 s4, s10, s4
	s_mul_i32 s8, s5, s7
	s_addc_u32 s5, s11, 0
	v_and_b32_e32 v0, 0xf0, v53
	v_mov_b32_e32 v1, 0
	v_lshl_add_u64 v[16:17], s[4:5], 0, v[0:1]
	v_add_u32_e32 v0, s2, v110
	v_max_i32_e32 v0, 0, v0
	v_lshlrev_b32_e32 v0, s6, v0
	v_add_u32_e32 v0, s3, v0
	v_ashrrev_i32_e32 v1, 31, v0
	v_lshlrev_b64 v[0:1], 11, v[0:1]
	v_add_u32_e32 v28, 0x200, v52
	v_lshl_add_u64 v[8:9], v[16:17], 0, v[0:1]
	v_ashrrev_i32_e32 v0, 4, v28
	v_add_u32_e32 v0, s2, v0
	v_max_i32_e32 v0, 0, v0
	v_lshlrev_b32_e32 v0, s6, v0
	v_add_u32_e32 v0, s3, v0
	v_ashrrev_i32_e32 v1, 31, v0
	v_lshlrev_b64 v[0:1], 11, v[0:1]
	v_add_u32_e32 v36, 0x400, v52
	v_lshl_add_u64 v[10:11], v[16:17], 0, v[0:1]
	global_load_dwordx4 v[0:3], v[8:9], off
	global_load_dwordx4 v[4:7], v[10:11], off
	v_ashrrev_i32_e32 v8, 4, v36
	v_add_u32_e32 v8, s2, v8
	v_max_i32_e32 v8, 0, v8
	v_lshlrev_b32_e32 v8, s6, v8
	v_add_u32_e32 v8, s3, v8
	v_ashrrev_i32_e32 v9, 31, v8
	v_lshlrev_b64 v[8:9], 11, v[8:9]
	v_add_u32_e32 v37, 0x600, v52
	v_lshl_add_u64 v[18:19], v[16:17], 0, v[8:9]
	v_ashrrev_i32_e32 v8, 4, v37
	v_add_u32_e32 v8, s2, v8
	v_max_i32_e32 v8, 0, v8
	v_lshlrev_b32_e32 v8, s6, v8
	v_add_u32_e32 v8, s3, v8
	v_ashrrev_i32_e32 v9, 31, v8
	v_lshlrev_b64 v[8:9], 11, v[8:9]
	v_add_u32_e32 v44, 0x800, v52
	v_lshl_add_u64 v[20:21], v[16:17], 0, v[8:9]
	global_load_dwordx4 v[8:11], v[18:19], off
	global_load_dwordx4 v[12:15], v[20:21], off
	v_ashrrev_i32_e32 v18, 4, v44
	v_add_u32_e32 v18, s2, v18
	v_max_i32_e32 v18, 0, v18
	v_lshlrev_b32_e32 v18, s6, v18
	v_add_u32_e32 v18, s3, v18
	v_ashrrev_i32_e32 v19, 31, v18
	v_lshlrev_b64 v[18:19], 11, v[18:19]
	v_add_u32_e32 v45, 0xa00, v52
	v_lshl_add_u64 v[24:25], v[16:17], 0, v[18:19]
	v_ashrrev_i32_e32 v18, 4, v45
	v_add_u32_e32 v18, s2, v18
	v_max_i32_e32 v18, 0, v18
	v_lshlrev_b32_e32 v18, s6, v18
	v_add_u32_e32 v18, s3, v18
	v_ashrrev_i32_e32 v19, 31, v18
	s_add_u32 s0, s85, s0
	v_lshlrev_b64 v[18:19], 11, v[18:19]
	s_addc_u32 s1, s86, s1
	s_lshl_b32 s3, s8, 1
	v_lshl_add_u64 v[26:27], v[16:17], 0, v[18:19]
	global_load_dwordx4 v[16:19], v[24:25], off
	global_load_dwordx4 v[20:23], v[26:27], off
	s_add_u32 s0, s0, s3
	v_min_i32_e32 v25, 0xcff, v52
	s_mov_b32 s3, 0x4ec4ec4f
	v_mul_hi_i32 v24, v25, s3
	v_lshrrev_b32_e32 v26, 31, v24
	v_ashrrev_i32_e32 v24, 3, v24
	v_add_u32_e32 v24, v24, v26
	v_mul_lo_u32 v26, v24, 26
	v_sub_u32_e32 v25, v25, v26
	v_lshl_add_u32 v25, v25, 3, s2
	s_addc_u32 s1, s1, 0
	s_add_i32 s7, s7, -8
	v_max_i32_e32 v25, 0, v25
	v_min_i32_e32 v26, s7, v25
	v_ashrrev_i32_e32 v25, 31, v24
	v_lshlrev_b64 v[24:25], 12, v[24:25]
	v_lshl_add_u64 v[24:25], s[0:1], 0, v[24:25]
	v_ashrrev_i32_e32 v27, 31, v26
	v_lshl_add_u64 v[32:33], v[26:27], 1, v[24:25]
	v_min_i32_e32 v25, 0xcff, v28
	v_mul_hi_i32 v24, v25, s3
	v_lshrrev_b32_e32 v26, 31, v24
	v_ashrrev_i32_e32 v24, 3, v24
	v_add_u32_e32 v24, v24, v26
	v_mul_lo_u32 v26, v24, 26
	v_sub_u32_e32 v25, v25, v26
	v_lshl_add_u32 v25, v25, 3, s2
	v_max_i32_e32 v25, 0, v25
	v_min_i32_e32 v26, s7, v25
	v_ashrrev_i32_e32 v25, 31, v24
	v_lshlrev_b64 v[24:25], 12, v[24:25]
	v_lshl_add_u64 v[24:25], s[0:1], 0, v[24:25]
	v_ashrrev_i32_e32 v27, 31, v26
	v_lshl_add_u64 v[34:35], v[26:27], 1, v[24:25]
	global_load_dwordx4 v[24:27], v[32:33], off
	global_load_dwordx4 v[28:31], v[34:35], off
	v_min_i32_e32 v33, 0xcff, v36
	v_mul_hi_i32 v32, v33, s3
	v_lshrrev_b32_e32 v34, 31, v32
	v_ashrrev_i32_e32 v32, 3, v32
	v_add_u32_e32 v32, v32, v34
	v_mul_lo_u32 v34, v32, 26
	v_sub_u32_e32 v33, v33, v34
	v_lshl_add_u32 v33, v33, 3, s2
	v_max_i32_e32 v33, 0, v33
	v_min_i32_e32 v34, s7, v33
	v_ashrrev_i32_e32 v33, 31, v32
	v_lshlrev_b64 v[32:33], 12, v[32:33]
	v_lshl_add_u64 v[32:33], s[0:1], 0, v[32:33]
	v_ashrrev_i32_e32 v35, 31, v34
	v_lshl_add_u64 v[40:41], v[34:35], 1, v[32:33]
	v_min_i32_e32 v33, 0xcff, v37
	v_mul_hi_i32 v32, v33, s3
	v_lshrrev_b32_e32 v34, 31, v32
	v_ashrrev_i32_e32 v32, 3, v32
	v_add_u32_e32 v32, v32, v34
	v_mul_lo_u32 v34, v32, 26
	v_sub_u32_e32 v33, v33, v34
	v_lshl_add_u32 v33, v33, 3, s2
	v_max_i32_e32 v33, 0, v33
	v_min_i32_e32 v34, s7, v33
	v_ashrrev_i32_e32 v33, 31, v32
	v_lshlrev_b64 v[32:33], 12, v[32:33]
	v_lshl_add_u64 v[32:33], s[0:1], 0, v[32:33]
	v_ashrrev_i32_e32 v35, 31, v34
	v_lshl_add_u64 v[42:43], v[34:35], 1, v[32:33]
	global_load_dwordx4 v[32:35], v[40:41], off
	global_load_dwordx4 v[36:39], v[42:43], off
	v_min_i32_e32 v41, 0xcff, v44
	v_mul_hi_i32 v40, v41, s3
	v_lshrrev_b32_e32 v42, 31, v40
	v_ashrrev_i32_e32 v40, 3, v40
	v_add_u32_e32 v40, v40, v42
	v_mul_lo_u32 v42, v40, 26
	v_sub_u32_e32 v41, v41, v42
	v_lshl_add_u32 v41, v41, 3, s2
	v_max_i32_e32 v41, 0, v41
	v_min_i32_e32 v42, s7, v41
	v_ashrrev_i32_e32 v41, 31, v40
	v_lshlrev_b64 v[40:41], 12, v[40:41]
	v_lshl_add_u64 v[40:41], s[0:1], 0, v[40:41]
	v_ashrrev_i32_e32 v43, 31, v42
	v_lshl_add_u64 v[48:49], v[42:43], 1, v[40:41]
	v_min_i32_e32 v41, 0xcff, v45
	v_mul_hi_i32 v40, v41, s3
	v_lshrrev_b32_e32 v42, 31, v40
	v_ashrrev_i32_e32 v40, 3, v40
	v_add_u32_e32 v40, v40, v42
	v_mul_lo_u32 v42, v40, 26
	v_sub_u32_e32 v41, v41, v42
	v_lshl_add_u32 v41, v41, 3, s2
	v_max_i32_e32 v41, 0, v41
	v_min_i32_e32 v42, s7, v41
	v_ashrrev_i32_e32 v41, 31, v40
	v_lshlrev_b64 v[40:41], 12, v[40:41]
	v_lshl_add_u64 v[40:41], s[0:1], 0, v[40:41]
	v_ashrrev_i32_e32 v43, 31, v42
	v_lshl_add_u64 v[50:51], v[42:43], 1, v[40:41]
	global_load_dwordx4 v[40:43], v[48:49], off
	global_load_dwordx4 v[44:47], v[50:51], off
	v_min_i32_e32 v48, 0xff, v52
	v_add_u32_e32 v49, 0xc00, v48
	v_mul_hi_i32 v48, v49, s3
	v_lshrrev_b32_e32 v50, 31, v48
	v_ashrrev_i32_e32 v48, 3, v48
	v_add_u32_e32 v48, v48, v50
	v_mul_lo_u32 v50, v48, 26
	v_sub_u32_e32 v49, v49, v50
	v_lshl_add_u32 v49, v49, 3, s2
	v_max_i32_e32 v49, 0, v49
	v_min_i32_e32 v50, s7, v49
	v_ashrrev_i32_e32 v49, 31, v48
	v_lshlrev_b64 v[48:49], 12, v[48:49]
	v_lshl_add_u64 v[48:49], s[0:1], 0, v[48:49]
	v_ashrrev_i32_e32 v51, 31, v50
	v_lshl_add_u64 v[48:49], v[50:51], 1, v[48:49]
	global_load_dwordx4 v[48:51], v[48:49], off

.LBB0_1732:
	s_waitcnt vmcnt(40)
	v_lshrrev_b32_e32 v52, 16, v27
	v_lshrrev_b32_e32 v53, 16, v26
	v_lshrrev_b32_e32 v54, 16, v25
	v_lshrrev_b32_e32 v55, 16, v24
	s_barrier
	ds_write_b128 v123, v[0:3]
	ds_write_b128 v124, v[4:7]
	ds_write_b128 v125, v[8:11]
	ds_write_b128 v126, v[12:15]
	ds_write_b128 v127, v[16:19]
	ds_write_b128 v128, v[20:23]
	s_and_saveexec_b64 s[16:17], s[2:3]
	v_perm_b32 v56, v55, v24, s60
	v_perm_b32 v57, v54, v25, s60
	v_perm_b32 v58, v53, v26, s60
	v_perm_b32 v59, v52, v27, s60
	ds_write_b128 v129, v[56:59] offset:52224
	s_or_b64 exec, exec, s[16:17]
	v_lshrrev_b32_e32 v56, 16, v31
	v_lshrrev_b32_e32 v57, 16, v30
	v_lshrrev_b32_e32 v58, 16, v29
	v_lshrrev_b32_e32 v59, 16, v28
	s_and_saveexec_b64 s[16:17], s[4:5]
	v_perm_b32 v60, v59, v28, s60
	v_perm_b32 v61, v58, v29, s60
	v_perm_b32 v62, v57, v30, s60
	v_perm_b32 v63, v56, v31, s60
	ds_write_b128 v130, v[60:63] offset:52224
	s_or_b64 exec, exec, s[16:17]
	v_lshrrev_b32_e32 v60, 16, v35
	v_lshrrev_b32_e32 v61, 16, v34
	v_lshrrev_b32_e32 v62, 16, v33
	v_lshrrev_b32_e32 v63, 16, v32
	s_and_saveexec_b64 s[16:17], s[6:7]
	v_perm_b32 v64, v63, v32, s60
	v_perm_b32 v65, v62, v33, s60
	v_perm_b32 v66, v61, v34, s60
	v_perm_b32 v67, v60, v35, s60
	ds_write_b128 v131, v[64:67] offset:52224
	s_or_b64 exec, exec, s[16:17]
	v_lshrrev_b32_e32 v64, 16, v39
	v_lshrrev_b32_e32 v65, 16, v38
	v_lshrrev_b32_e32 v66, 16, v37
	v_lshrrev_b32_e32 v67, 16, v36
	s_and_saveexec_b64 s[16:17], s[8:9]
	v_perm_b32 v68, v67, v36, s60
	v_perm_b32 v69, v66, v37, s60
	v_perm_b32 v70, v65, v38, s60
	v_perm_b32 v71, v64, v39, s60
	ds_write_b128 v132, v[68:71] offset:52224
	s_or_b64 exec, exec, s[16:17]
	v_lshrrev_b32_e32 v68, 16, v43
	v_lshrrev_b32_e32 v69, 16, v42
	v_lshrrev_b32_e32 v70, 16, v41
	v_lshrrev_b32_e32 v71, 16, v40
	s_and_saveexec_b64 s[16:17], s[10:11]
	v_perm_b32 v72, v71, v40, s60
	v_perm_b32 v73, v70, v41, s60
	v_perm_b32 v74, v69, v42, s60
	v_perm_b32 v75, v68, v43, s60
	ds_write_b128 v133, v[72:75] offset:52224
	s_or_b64 exec, exec, s[16:17]
	v_lshrrev_b32_e32 v72, 16, v47
	v_lshrrev_b32_e32 v73, 16, v46
	v_lshrrev_b32_e32 v74, 16, v45
	v_lshrrev_b32_e32 v75, 16, v44
	s_and_saveexec_b64 s[16:17], s[12:13]
	v_perm_b32 v76, v75, v44, s60
	v_perm_b32 v77, v74, v45, s60
	v_perm_b32 v78, v73, v46, s60
	v_perm_b32 v79, v72, v47, s60
	ds_write_b128 v134, v[76:79] offset:52224
	s_or_b64 exec, exec, s[16:17]
	v_lshrrev_b32_e32 v76, 16, v51
	v_lshrrev_b32_e32 v77, 16, v50
	v_lshrrev_b32_e32 v78, 16, v49
	v_lshrrev_b32_e32 v79, 16, v48
	s_and_saveexec_b64 s[16:17], s[14:15]
	v_perm_b32 v80, v79, v48, s60
	v_perm_b32 v81, v78, v49, s60
	v_perm_b32 v82, v77, v50, s60
	v_perm_b32 v83, v76, v51, s60
	ds_write_b128 v135, v[80:83] offset:52224
	s_or_b64 exec, exec, s[16:17]
	s_add_i32 s74, s36, s52
	s_cmp_ge_i32 s74, s33
	s_cselect_b64 s[48:49], -1, 0
	s_and_b64 vcc, exec, s[48:49]
	s_waitcnt lgkmcnt(0)
	s_barrier
	s_cbranch_vccnz .LBB0_1748
	s_add_i32 s98, s74, 0xfffffee0
	s_cmpk_lt_i32 s74, 0x9a8
	s_cselect_b32 s98, s74, s98
	s_add_i32 s99, s74, 0xffffff70
	s_cmpk_lt_i32 s74, 0x9c0
	s_cselect_b32 s98, s98, s99
	s_add_i32 s99, s74, 0xfffffc18
	s_cmpk_lt_i32 s74, 0xce0
	s_cselect_b32 s98, s98, s99
	s_cmp_eq_u32 s52, s77
	s_cselect_b32 s98, s74, s98
	s_add_i32 s0, s98, 0xffffff40
	s_ashr_i32 s0, s0, 5
	s_mul_hi_i32 s17, s0, 0x55555556
	s_lshr_b32 s18, s17, 31
	s_add_i32 s18, s17, s18
	s_mul_i32 s17, s18, 3
	s_sub_i32 s0, s0, s17
	s_lshl_b32 s20, s0, 1
	s_lshr_b32 s17, 32, s20
	s_and_b32 s16, s98, 31
	s_sub_i32 s22, 5, s20
	s_add_i32 s17, s17, -1
	s_lshr_b32 s22, s16, s22
	s_and_b32 s16, s17, s16
	s_lshl_b32 s23, s16, 6
	s_lshl_b32 s0, s0, 5
	s_and_b32 s16, s18, -8
	s_and_b32 s19, s18, 7
	s_add_i32 s0, s0, s16
	s_or_b32 s16, s0, s19
	s_lshl_b32 s0, s18, 8
	s_ashr_i32 s17, s16, 31
	s_and_b32 s0, s0, 0xfffff800
	s_lshr_b32 s21, 0x800, s20
	s_lshl_b64 s[16:17], s[16:17], 19
	s_addk_i32 s23, 0xff80
	s_or_b32 s18, s22, s0
	s_lshl_b32 s0, s19, 8
	s_mul_i32 s24, s22, s21
	v_lshl_add_u64 v[16:17], v[86:87], 0, s[0:1]
	s_add_u32 s0, s85, s16
	s_addc_u32 s17, s86, s17
	s_lshl_b32 s16, s24, 1
	s_add_u32 s16, s0, s16
	v_add_u32_e32 v24, s23, v116
	v_add_u32_e32 v32, s23, v118
	v_add_u32_e32 v40, s23, v120
	s_addc_u32 s17, s17, 0
	s_add_i32 s21, s21, -8
	v_max_i32_e32 v24, 0, v24
	v_max_i32_e32 v32, 0, v32
	v_max_i32_e32 v40, 0, v40
	v_add_u32_e32 v0, s23, v110
	v_add_u32_e32 v2, s23, v111
	v_add_u32_e32 v8, s23, v112
	v_add_u32_e32 v10, s23, v113
	v_add_u32_e32 v18, s23, v114
	v_add_u32_e32 v20, s23, v115
	v_min_i32_e32 v24, s21, v24
	v_min_i32_e32 v32, s21, v32
	v_min_i32_e32 v40, s21, v40
	v_max_i32_e32 v0, 0, v0
	v_max_i32_e32 v2, 0, v2
	v_max_i32_e32 v8, 0, v8
	v_max_i32_e32 v10, 0, v10
	v_max_i32_e32 v18, 0, v18
	v_max_i32_e32 v20, 0, v20
	v_lshl_add_u64 v[26:27], s[16:17], 0, v[88:89]
	v_ashrrev_i32_e32 v25, 31, v24
	v_lshl_add_u64 v[34:35], s[16:17], 0, v[92:93]
	v_ashrrev_i32_e32 v33, 31, v32
	v_lshl_add_u64 v[42:43], s[16:17], 0, v[96:97]
	v_ashrrev_i32_e32 v41, 31, v40
	v_lshlrev_b32_e32 v0, s20, v0
	v_lshlrev_b32_e32 v2, s20, v2
	v_lshlrev_b32_e32 v8, s20, v8
	v_lshlrev_b32_e32 v10, s20, v10
	v_lshlrev_b32_e32 v18, s20, v18
	v_lshlrev_b32_e32 v20, s20, v20
	v_lshl_add_u64 v[24:25], v[24:25], 1, v[26:27]
	v_add_u32_e32 v26, s23, v117
	v_lshl_add_u64 v[32:33], v[32:33], 1, v[34:35]
	v_add_u32_e32 v34, s23, v119
	v_lshl_add_u64 v[40:41], v[40:41], 1, v[42:43]
	v_add_u32_e32 v42, s23, v121
	v_add_u32_e32 v48, s23, v122
	v_add_u32_e32 v0, s18, v0
	v_add_u32_e32 v2, s18, v2
	v_add_u32_e32 v8, s18, v8
	v_add_u32_e32 v10, s18, v10
	v_add_u32_e32 v18, s18, v18
	v_add_u32_e32 v20, s18, v20
	v_max_i32_e32 v26, 0, v26
	v_max_i32_e32 v34, 0, v34
	v_max_i32_e32 v42, 0, v42
	v_max_i32_e32 v48, 0, v48
	v_ashrrev_i32_e32 v1, 31, v0
	v_ashrrev_i32_e32 v3, 31, v2
	v_ashrrev_i32_e32 v9, 31, v8
	v_ashrrev_i32_e32 v11, 31, v10
	v_ashrrev_i32_e32 v19, 31, v18
	v_ashrrev_i32_e32 v21, 31, v20
	v_min_i32_e32 v26, s21, v26
	v_min_i32_e32 v34, s21, v34
	v_min_i32_e32 v42, s21, v42
	v_min_i32_e32 v48, s21, v48
	v_lshlrev_b64 v[0:1], 11, v[0:1]
	v_lshlrev_b64 v[2:3], 11, v[2:3]
	v_lshlrev_b64 v[8:9], 11, v[8:9]
	v_lshlrev_b64 v[10:11], 11, v[10:11]
	v_lshlrev_b64 v[18:19], 11, v[18:19]
	v_lshlrev_b64 v[20:21], 11, v[20:21]
	v_lshl_add_u64 v[28:29], s[16:17], 0, v[90:91]
	v_ashrrev_i32_e32 v27, 31, v26
	v_lshl_add_u64 v[36:37], s[16:17], 0, v[94:95]
	v_ashrrev_i32_e32 v35, 31, v34
	v_lshl_add_u64 v[44:45], s[16:17], 0, v[98:99]
	v_ashrrev_i32_e32 v43, 31, v42
	v_lshl_add_u64 v[50:51], s[16:17], 0, v[100:101]
	v_ashrrev_i32_e32 v49, 31, v48
	v_lshl_add_u64 v[0:1], v[16:17], 0, v[0:1]
	v_lshl_add_u64 v[4:5], v[16:17], 0, v[2:3]
	v_lshl_add_u64 v[8:9], v[16:17], 0, v[8:9]
	v_lshl_add_u64 v[12:13], v[16:17], 0, v[10:11]
	v_lshl_add_u64 v[18:19], v[16:17], 0, v[18:19]
	v_lshl_add_u64 v[20:21], v[16:17], 0, v[20:21]
	v_lshl_add_u64 v[28:29], v[26:27], 1, v[28:29]
	v_lshl_add_u64 v[36:37], v[34:35], 1, v[36:37]
	v_lshl_add_u64 v[44:45], v[42:43], 1, v[44:45]
	v_lshl_add_u64 v[48:49], v[48:49], 1, v[50:51]
	s_branch .LBB0_1749

.LBB0_1749:
	s_add_i32 s98, s36, 0xfffffee0
	s_cmpk_lt_i32 s36, 0x9a8
	s_cselect_b32 s98, s36, s98
	s_add_i32 s99, s36, 0xffffff70
	s_cmpk_lt_i32 s36, 0x9c0
	s_cselect_b32 s98, s98, s99
	s_add_i32 s99, s36, 0xfffffc18
	s_cmpk_lt_i32 s36, 0xce0
	s_cselect_b32 s98, s98, s99
	s_cmp_eq_u32 s52, s77
	s_cselect_b32 s98, s36, s98
	s_add_i32 s0, s98, 0xffffff40
	s_ashr_i32 s0, s0, 5
	s_mul_hi_i32 s17, s0, 0x55555556
	s_lshr_b32 s18, s17, 31
	s_add_i32 s20, s17, s18
	s_mul_i32 s17, s20, 3
	s_sub_i32 s21, s0, s17
	s_lshl_b32 s0, s21, 1
	s_lshr_b32 s17, 32, s0
	v_mov_b32_e32 v52, v244
	s_and_b32 s16, s98, 31
	s_sub_i32 s18, 5, s0
	s_add_i32 s17, s17, -1
	s_lshr_b32 s22, s16, s18
	s_and_b32 s28, s17, s16
	s_lshl_b32 s16, s20, 2
	v_ashrrev_i32_e32 v53, 6, v52
	v_and_b32_e32 v138, 15, v52
	v_bfe_u32 v58, v52, 4, 2
	v_ashrrev_i32_e32 v52, 7, v52
	s_and_b32 s16, s16, 28
	s_lshl_b32 s75, s28, 6
	v_add_u32_e32 v52, s16, v52
	s_mul_i32 s16, s21, 0x4200000
	s_mul_hi_i32 s17, s21, 0x4200000
	s_add_u32 s16, s54, s16
	s_addc_u32 s17, s55, s17
	s_mul_i32 s18, s21, 0x108000
	s_mul_hi_i32 s19, s21, 0x108000
	s_add_u32 s18, s58, s18
	s_addc_u32 s19, s59, s19
	s_lshl_b32 s20, s20, 8
	s_and_b32 s20, s20, 0xfffff800
	s_or_b32 s76, s22, s20
	s_lshl_b32 s20, s21, 12
	v_mul_lo_u32 v54, v53, s61
	s_ashr_i32 s21, s20, 31
	v_add_u32_e32 v59, 0x1a400, v54
	v_lshlrev_b32_e32 v53, 5, v53
	s_lshl_b64 s[20:21], s[20:21], 1
	v_lshlrev_b32_e32 v54, 7, v52
	v_lshlrev_b32_e32 v141, 2, v58
	v_and_b32_e32 v139, 32, v53
	s_add_u32 s20, s80, s20
	v_ashrrev_i32_e32 v55, 31, v54
	v_sub_u32_e32 v60, v141, v138
	v_ashrrev_i32_e32 v53, 31, v52
	s_addc_u32 s21, s81, s21
	v_lshlrev_b64 v[54:55], 1, v[54:55]
	v_lshl_add_u64 v[106:107], v[52:53], 2, s[18:19]
	v_add_u32_e32 v52, 1, v60
	v_lshl_add_u64 v[56:57], s[20:21], 0, v[54:55]
	v_cmp_gt_u32_e64 s[20:21], s63, v52
	v_add_u32_e32 v52, 0x82, v60
	v_add_u32_e32 v61, 0x80, v60
	v_cmp_gt_u32_e64 s[34:35], s63, v52
	v_add_u32_e32 v52, 2, v60
	s_cmp_gt_u32 s28, 1
	v_cmp_gt_u32_e32 vcc, s63, v61
	v_cmp_gt_u32_e64 s[22:23], s63, v52
	v_add_u32_e32 v52, 0x83, v60
	s_cselect_b64 s[40:41], -1, 0
	v_lshlrev_b32_e32 v84, 4, v58
	v_cmp_gt_u32_e64 s[36:37], s63, v52
	v_add_u32_e32 v52, 3, v60
	s_and_b64 s[26:27], vcc, s[40:41]
	v_lshl_add_u64 v[102:103], v[56:57], 0, v[84:85]
	v_mad_u32_u24 v62, v138, s62, v59
	v_lshl_add_u64 v[54:55], s[16:17], 0, v[54:55]
	v_lshlrev_b32_e32 v56, 1, v138
	v_mov_b32_e32 v57, v85
	v_cmp_lt_u32_e64 s[30:31], s64, v60
	v_cmp_gt_u32_e64 s[24:25], s63, v52
	v_mad_u32_u24 v52, v58, s65, v59
	s_cmp_eq_u32 s28, 0
	v_lshlrev_b32_e32 v140, 3, v58
	v_lshl_add_u64 v[104:105], v[54:55], 0, v[56:57]
	s_mov_b32 s38, 0
	v_cmp_eq_u32_e64 s[16:17], 0, v138
	v_cmp_gt_u32_e64 s[18:19], s63, v60
	v_or_b32_e32 v142, v52, v56
	v_mul_u32_u24_e32 v143, 0x1b0, v138
	s_cselect_b64 s[28:29], -1, 0
	s_and_b64 s[30:31], s[30:31], s[40:41]
	s_and_b64 s[34:35], s[34:35], s[40:41]
	s_and_b64 s[36:37], s[36:37], s[40:41]
	s_mov_b64 s[50:51], -1
	v_add_u32_e32 v144, v62, v84
	s_branch .LBB0_1751
